# layer-0 pa/pb/o weight conversion moved from the L0 up1 slot to the L0 in-proj slot (on top of the rebalanced layer-1 slots)
# baseline (speedup 1.0000x reference)
; #define LAS __attribute__((address_space(3)))
; __device__ __forceinline__ void prologue(const kptr_t kp, LAS float* scr, int gw, int NGW, int lane) {
;     unsigned char* ws = KPTR(unsigned char, 23);
;     for (int it = gw; it < IT_TOTAL; it += NGW) {
;         int r = it;
.LBB0_239:
	s_cmp_lt_u32 s2, 44
	s_cbranch_scc1 .Lslot_1_skip
	v_writelane_b32 v250, s3, 0
	v_writelane_b32 v250, s4, 1
	v_writelane_b32 v250, s5, 2
	v_writelane_b32 v250, s6, 3
	v_writelane_b32 v250, s7, 4
	v_writelane_b32 v250, s8, 5
	v_writelane_b32 v250, s9, 6
	v_writelane_b32 v250, s10, 7
	v_writelane_b32 v250, s11, 8
	v_writelane_b32 v250, s12, 9
	v_writelane_b32 v250, s13, 10
	v_writelane_b32 v250, s14, 11
	v_writelane_b32 v250, s15, 12
	v_writelane_b32 v250, s16, 13
	v_writelane_b32 v250, s17, 14
	v_writelane_b32 v250, s18, 15
	v_writelane_b32 v250, s19, 16
	v_writelane_b32 v250, s20, 17
	v_writelane_b32 v250, s21, 18
	v_writelane_b32 v250, s22, 19
	v_writelane_b32 v250, s23, 20
	v_writelane_b32 v250, s24, 21
	v_writelane_b32 v250, s25, 22
	v_writelane_b32 v250, s26, 23
	v_writelane_b32 v250, s27, 24
	v_writelane_b32 v250, s28, 25
	v_writelane_b32 v250, s29, 26
	v_writelane_b32 v250, s30, 27
	v_writelane_b32 v250, s31, 28
	v_writelane_b32 v250, s32, 29
	v_writelane_b32 v250, s33, 30
	v_writelane_b32 v250, s34, 31
	v_writelane_b32 v250, s35, 32
	v_writelane_b32 v250, s36, 33
	v_writelane_b32 v250, s37, 34
	v_writelane_b32 v250, s38, 35
	v_writelane_b32 v250, s39, 36
	v_writelane_b32 v250, s40, 37
	v_writelane_b32 v250, s41, 38
	v_writelane_b32 v250, s42, 39
	v_writelane_b32 v250, s43, 40
	v_writelane_b32 v250, s44, 41
	v_writelane_b32 v250, s45, 42
	v_writelane_b32 v250, s46, 43
	v_writelane_b32 v250, s47, 44
	v_writelane_b32 v250, s48, 45
	v_writelane_b32 v250, s49, 46
	v_writelane_b32 v250, s50, 47
	v_writelane_b32 v250, s51, 48
	v_writelane_b32 v250, s52, 49
	v_writelane_b32 v250, s53, 50
	v_writelane_b32 v250, s54, 51
	v_writelane_b32 v250, s55, 52
	v_writelane_b32 v250, s56, 53
	v_writelane_b32 v250, s57, 54
	v_writelane_b32 v250, s58, 55
	v_writelane_b32 v250, s59, 56
	v_writelane_b32 v250, s60, 57
	v_writelane_b32 v250, s61, 58
	v_writelane_b32 v250, s62, 59
	v_writelane_b32 v250, s63, 60
	v_writelane_b32 v250, s64, 61
	v_writelane_b32 v250, s65, 62
	v_writelane_b32 v250, s66, 63
	v_writelane_b32 v251, s67, 0
	v_writelane_b32 v251, s68, 1
	v_writelane_b32 v251, s69, 2
	v_writelane_b32 v251, s70, 3
	v_writelane_b32 v251, s71, 4
	v_writelane_b32 v251, s72, 5
	v_writelane_b32 v251, s73, 6
	v_writelane_b32 v251, s74, 7
	v_writelane_b32 v251, s75, 8
	v_writelane_b32 v251, s76, 9
	v_writelane_b32 v251, s77, 10
	v_writelane_b32 v251, s78, 11
	v_writelane_b32 v251, s79, 12
	v_writelane_b32 v251, s80, 13
	v_writelane_b32 v251, s81, 14
	v_writelane_b32 v251, s82, 15
	v_writelane_b32 v251, s83, 16
	v_writelane_b32 v251, s84, 17
	v_writelane_b32 v251, s85, 18
	v_writelane_b32 v251, s86, 19
	v_writelane_b32 v251, s87, 20
	v_writelane_b32 v251, s88, 21
	v_writelane_b32 v251, s89, 22
	v_writelane_b32 v251, s90, 23
	v_writelane_b32 v251, s91, 24
	v_writelane_b32 v251, s92, 25
	v_writelane_b32 v251, s93, 26
	v_writelane_b32 v251, s94, 27
	v_writelane_b32 v251, s95, 28
	v_writelane_b32 v251, s96, 29
	v_writelane_b32 v251, s97, 30
	v_mov_b32_e32 v236, v200
	v_mov_b32_e32 v237, v201
	v_mov_b32_e32 v238, v202
	v_mov_b32_e32 v239, v203
	v_mov_b32_e32 v240, v204
	v_mov_b32_e32 v241, v205
	v_mov_b32_e32 v242, v206
	v_mov_b32_e32 v243, v207
	v_mov_b32_e32 v244, v208
	v_mov_b32_e32 v245, v209
	v_mov_b32_e32 v246, v210
	v_mov_b32_e32 v247, v211
	s_mov_b32 s98, 0xe20
	s_mov_b32 s99, 0x6a0
	s_mov_b32 s100, 0x1e00
	s_mov_b32 s101, 11
	s_branch .Lcv_entry

; #define LAS __attribute__((address_space(3)))
; __device__ __forceinline__ void prologue(const kptr_t kp, LAS float* scr, int gw, int NGW, int lane) {
;     unsigned char* ws = KPTR(unsigned char, 23);
;     for (int it = gw; it < IT_TOTAL; it += NGW) {
;         int r = it;
.LBB0_847:
	s_cmp_lt_u32 s2, 36
	s_cbranch_scc1 .Lslot_2_skip
	v_writelane_b32 v250, s3, 0
	v_writelane_b32 v250, s4, 1
	v_writelane_b32 v250, s5, 2
	v_writelane_b32 v250, s6, 3
	v_writelane_b32 v250, s7, 4
	v_writelane_b32 v250, s8, 5
	v_writelane_b32 v250, s9, 6
	v_writelane_b32 v250, s10, 7
	v_writelane_b32 v250, s11, 8
	v_writelane_b32 v250, s12, 9
	v_writelane_b32 v250, s13, 10
	v_writelane_b32 v250, s14, 11
	v_writelane_b32 v250, s15, 12
	v_writelane_b32 v250, s16, 13
	v_writelane_b32 v250, s17, 14
	v_writelane_b32 v250, s18, 15
	v_writelane_b32 v250, s19, 16
	v_writelane_b32 v250, s20, 17
	v_writelane_b32 v250, s21, 18
	v_writelane_b32 v250, s22, 19
	v_writelane_b32 v250, s23, 20
	v_writelane_b32 v250, s24, 21
	v_writelane_b32 v250, s25, 22
	v_writelane_b32 v250, s26, 23
	v_writelane_b32 v250, s27, 24
	v_writelane_b32 v250, s28, 25
	v_writelane_b32 v250, s29, 26
	v_writelane_b32 v250, s30, 27
	v_writelane_b32 v250, s31, 28
	v_writelane_b32 v250, s32, 29
	v_writelane_b32 v250, s33, 30
	v_writelane_b32 v250, s34, 31
	v_writelane_b32 v250, s35, 32
	v_writelane_b32 v250, s36, 33
	v_writelane_b32 v250, s37, 34
	v_writelane_b32 v250, s38, 35
	v_writelane_b32 v250, s39, 36
	v_writelane_b32 v250, s40, 37
	v_writelane_b32 v250, s41, 38
	v_writelane_b32 v250, s42, 39
	v_writelane_b32 v250, s43, 40
	v_writelane_b32 v250, s44, 41
	v_writelane_b32 v250, s45, 42
	v_writelane_b32 v250, s46, 43
	v_writelane_b32 v250, s47, 44
	v_writelane_b32 v250, s48, 45
	v_writelane_b32 v250, s49, 46
	v_writelane_b32 v250, s50, 47
	v_writelane_b32 v250, s51, 48
	v_writelane_b32 v250, s52, 49
	v_writelane_b32 v250, s53, 50
	v_writelane_b32 v250, s54, 51
	v_writelane_b32 v250, s55, 52
	v_writelane_b32 v250, s56, 53
	v_writelane_b32 v250, s57, 54
	v_writelane_b32 v250, s58, 55
	v_writelane_b32 v250, s59, 56
	v_writelane_b32 v250, s60, 57
	v_writelane_b32 v250, s61, 58
	v_writelane_b32 v250, s62, 59
	v_writelane_b32 v250, s63, 60
	v_writelane_b32 v250, s64, 61
	v_writelane_b32 v250, s65, 62
	v_writelane_b32 v250, s66, 63
	v_writelane_b32 v251, s67, 0
	v_writelane_b32 v251, s68, 1
	v_writelane_b32 v251, s69, 2
	v_writelane_b32 v251, s70, 3
	v_writelane_b32 v251, s71, 4
	v_writelane_b32 v251, s72, 5
	v_writelane_b32 v251, s73, 6
	v_writelane_b32 v251, s74, 7
	v_writelane_b32 v251, s75, 8
	v_writelane_b32 v251, s76, 9
	v_writelane_b32 v251, s77, 10
	v_writelane_b32 v251, s78, 11
	v_writelane_b32 v251, s79, 12
	v_writelane_b32 v251, s80, 13
	v_writelane_b32 v251, s81, 14
	v_writelane_b32 v251, s82, 15
	v_writelane_b32 v251, s83, 16
	v_writelane_b32 v251, s84, 17
	v_writelane_b32 v251, s85, 18
	v_writelane_b32 v251, s86, 19
	v_writelane_b32 v251, s87, 20
	v_writelane_b32 v251, s88, 21
	v_writelane_b32 v251, s89, 22
	v_writelane_b32 v251, s90, 23
	v_writelane_b32 v251, s91, 24
	v_writelane_b32 v251, s92, 25
	v_writelane_b32 v251, s93, 26
	v_writelane_b32 v251, s94, 27
	v_writelane_b32 v251, s95, 28
	v_writelane_b32 v251, s96, 29
	v_writelane_b32 v251, s97, 30
	v_mov_b32_e32 v236, v200
	v_mov_b32_e32 v237, v201
	v_mov_b32_e32 v238, v202
	v_mov_b32_e32 v239, v203
	v_mov_b32_e32 v240, v204
	v_mov_b32_e32 v241, v205
	v_mov_b32_e32 v242, v206
	v_mov_b32_e32 v243, v207
	v_mov_b32_e32 v244, v208
	v_mov_b32_e32 v245, v209
	v_mov_b32_e32 v246, v210
	v_mov_b32_e32 v247, v211
	s_mov_b32 s98, 0x1ce0
	s_mov_b32 s99, 0x6e0
	s_mov_b32 s100, 0x3b00
	s_mov_b32 s101, 12
	s_branch .Lcv_entry
